# v24 + layer-0 OUT/GU2 weight conversion moved from the prologue into the GEMM tail slots (item ranges rebalanced)
# speedup vs baseline: 1.0095x; 1.0095x over previous
; #define LAS __attribute__((address_space(3)))
; __device__ __forceinline__ void convert_range(unsigned char* lds, int lo, int hi, int w, int nworkers, int wave, int lane) {
;     const XItem* tab = (const XItem*)(lds + 8 * 16640);
;     LAS float* scr = (LAS float*)((LAS unsigned char*)lds + wave * 16640);
;     int it = lo + w; if (it >= hi) return;
;     f32x4 v[16]; float gv[16]; ItemPos p = item_load(tab, it, lane, v, gv);
; __global__ void __launch_bounds__(NTHREADS, 2) mega_fwd(KArgs a_unused) {
;     ...
;         if (((32 * 44) % G != 0) && ((32 * 18) % G != 0)) { convert_range(lds, 0, 5632, gw, NGW, wave, lane); convert_range(lds, 10752, 17408, gw, NGW, wave, lane); convert_range(lds, 21248, ITEMS_L, gw, NGW, wave, lane); convert_range(lds, ITEMS_L + 21248, 2 * ITEMS_L, gw, NGW, wave, lane); }
.LBB0_88:
	s_cmpk_gt_i32 s12, -1
	s_cbranch_scc1 .LBB0_157
	s_add_i32 s20, s12, 0x2a00
	s_mov_b32 s0, s20
	s_mov_b32 s1, 2
	s_mov_b32 s2, 1
	s_mov_b32 s3, 0
	v_bfrev_b32_e32 v2, 1
	v_bfrev_b32_e32 v3, 1

; #define LAS __attribute__((address_space(3)))
; #define GW_DECL const int wv_ = launder_s(g_wave), lane = opaque_lane(), tid = (wv_ << 6) | lane, gw = BXL() * NWAVES + wv_; (void)tid; (void)lane; (void)gw
; #define BXL() ({ int _b = bx; asm volatile("" : "+s"(_b)); _b; })
; __device__ __forceinline__ void convert_range(unsigned char* lds, int lo, int hi, int w, int nworkers, int wave, int lane) {
;     const XItem* tab = (const XItem*)(lds + 8 * 16640);
;     LAS float* scr = (LAS float*)((LAS unsigned char*)lds + wave * 16640);
;     int it = lo + w; if (it >= hi) return;
;     f32x4 v[16]; float gv[16]; ItemPos p = item_load(tab, it, lane, v, gv);
; __global__ void __launch_bounds__(NTHREADS, 2) mega_fwd(KArgs a_unused) {
;     ...
;           if (((32 * 44) % G != 0) && ((32 * 18) % G != 0)) { const int rem_ = (32 * 44) % G; const int bxt_ = BXL(); if (rem_ != 0 && bxt_ >= rem_) { GW_DECL; convert_range(lds, (l == 0 ? 5632 : ITEMS_L + 5632), (l == 0 ? 10752 : ITEMS_L + 10752), (bxt_ - rem_) * NWAVES + wv_, (G - rem_) * NWAVES, wv_, lane); __syncthreads(); } }
.LBB0_479:
	v_readlane_b32 s2, v255, 5
	v_readlane_b32 s3, v255, 6
	s_andn2_b64 vcc, exec, s[2:3]
	s_mov_b32 s4, s68
	v_cndmask_b32_e64 v0, 0, 1, s[2:3]
	v_readlane_b32 s2, v255, 11
	v_readlane_b32 s3, v255, 12
	v_cmp_ne_u32_e64 s[6:7], 1, v0
	s_nop 0
	v_cndmask_b32_e64 v0, 0, 1, s[2:3]
	v_cmp_ne_u32_e64 s[2:3], 1, v0
	s_nop 1
	v_writelane_b32 v255, s2, 39
	s_nop 1
	v_writelane_b32 v255, s3, 40
	s_cbranch_vccnz .LBB0_552
	v_readlane_b32 s2, v255, 39
	v_readlane_b32 s3, v255, 40
	s_and_b64 vcc, exec, s[2:3]
	s_cbranch_vccnz .LBB0_552
	v_readlane_b32 s2, v255, 7
	v_readlane_b32 s1, v255, 4
	s_cmp_lt_i32 s2, s1
	v_readlane_b32 s3, v255, 8
	s_cbranch_scc1 .LBB0_552
	v_readlane_b32 s4, v255, 7
	v_readlane_b32 s5, v255, 8
	s_mov_b32 s3, s4
	v_readlane_b32 s4, v255, 29
	v_readlane_b32 s5, v255, 30
	s_and_b64 s[4:5], s[4:5], exec
	s_movk_i32 s5, 0x2e00
	s_movk_i32 s4, 0x1600
	s_cselect_b32 s14, s5, 0x7d80
	v_readlane_b32 s5, v255, 4
	s_cselect_b32 s4, s4, 0x6980
	s_sub_i32 s2, s2, s5
	s_lshl_b32 s2, s2, 3
	s_mov_b32 s1, s64
	s_add_i32 s2, s2, s4
	s_add_i32 s15, s2, s1
	s_cmp_ge_i32 s15, s14
	v_mov_b32 v0, 0
	s_cbranch_scc1 .LBB0_551
	s_mov_b32 s2, s15
	s_mov_b32 s3, 2
	s_mov_b32 s4, 1
	s_mov_b32 s5, 0
	v_bfrev_b32_e32 v2, 1
	v_bfrev_b32_e32 v3, 1

; #define LAS __attribute__((address_space(3)))
; #define GW_DECL const int wv_ = launder_s(g_wave), lane = opaque_lane(), tid = (wv_ << 6) | lane, gw = BXL() * NWAVES + wv_; (void)tid; (void)lane; (void)gw
; #define BXL() ({ int _b = bx; asm volatile("" : "+s"(_b)); _b; })
; __device__ __forceinline__ void convert_range(unsigned char* lds, int lo, int hi, int w, int nworkers, int wave, int lane) {
;     const XItem* tab = (const XItem*)(lds + 8 * 16640);
;     LAS float* scr = (LAS float*)((LAS unsigned char*)lds + wave * 16640);
;     int it = lo + w; if (it >= hi) return;
;     f32x4 v[16]; float gv[16]; ItemPos p = item_load(tab, it, lane, v, gv);
; __global__ void __launch_bounds__(NTHREADS, 2) mega_fwd(KArgs a_unused) {
;     ...
;           if (((32 * 44) % G != 0) && ((32 * 18) % G != 0)) { const int rem_ = (32 * 18) % G; const int bxt_ = BXL(); if (rem_ != 0 && bxt_ >= rem_) { GW_DECL; convert_range(lds, (l == 0 ? 17408 : ITEMS_L + 10752), (l == 0 ? 21248 : ITEMS_L + 17408), (bxt_ - rem_) * NWAVES + wv_, (G - rem_) * NWAVES, wv_, lane); convert_range(lds, (l == 0 ? ITEMS_L : 0), (l == 0 ? ITEMS_L + 2816 : 0), (bxt_ - rem_) * NWAVES + wv_, (G - rem_) * NWAVES, wv_, lane); __syncthreads(); } } }
.LBB0_742:
	s_and_b64 vcc, exec, s[6:7]
	s_cbranch_vccnz .LBB0_884
	v_readlane_b32 s2, v255, 39
	v_readlane_b32 s3, v255, 40
	s_and_b64 vcc, exec, s[2:3]
	s_cbranch_vccnz .LBB0_884
	v_readlane_b32 s2, v255, 7
	s_mov_b32 s1, s2
	v_readlane_b32 s2, v255, 13
	s_cmp_lt_i32 s1, s2
	v_readlane_b32 s3, v255, 8
	s_cbranch_scc1 .LBB0_884
	v_readlane_b32 s2, v255, 7
	v_readlane_b32 s3, v255, 8
	s_mov_b32 s5, s2
	v_readlane_b32 s2, v255, 29
	v_readlane_b32 s3, v255, 30
	s_and_b64 s[2:3], s[2:3], exec
	s_movk_i32 s3, 0x4c00
	s_movk_i32 s2, 0x2e00
	s_cselect_b32 s16, s3, 0x9780
	v_readlane_b32 s3, v255, 13
	s_mov_b32 s4, s64
	s_cselect_b32 s2, s2, 0x7d80
	s_sub_i32 s1, s1, s3
	s_lshl_b32 s1, s1, 3
	v_mov_b32 v0, 0
	s_add_i32 s15, s4, s1
	s_mulk_i32 s4, 0x4100
	v_mbcnt_lo_u32_b32 v0, -1, v0
	s_add_i32 s14, s4, 0
	s_add_i32 s20, s15, s2
	v_mbcnt_hi_u32_b32 v96, -1, v0
	s_cmp_ge_i32 s20, s16
	s_cbranch_scc1 .LBB0_814
	s_mov_b32 s1, s20
	s_mov_b32 s2, 2
	s_mov_b32 s3, 1
	s_mov_b32 s4, 0
	v_bfrev_b32_e32 v0, 1
	v_bfrev_b32_e32 v2, 1

; #define LAS __attribute__((address_space(3)))
; #define GW_DECL const int wv_ = launder_s(g_wave), lane = opaque_lane(), tid = (wv_ << 6) | lane, gw = BXL() * NWAVES + wv_; (void)tid; (void)lane; (void)gw
; #define BXL() ({ int _b = bx; asm volatile("" : "+s"(_b)); _b; })
; __device__ __forceinline__ void convert_range(unsigned char* lds, int lo, int hi, int w, int nworkers, int wave, int lane) {
;     const XItem* tab = (const XItem*)(lds + 8 * 16640);
;     LAS float* scr = (LAS float*)((LAS unsigned char*)lds + wave * 16640);
;     int it = lo + w; if (it >= hi) return;
;     f32x4 v[16]; float gv[16]; ItemPos p = item_load(tab, it, lane, v, gv);
; __global__ void __launch_bounds__(NTHREADS, 2) mega_fwd(KArgs a_unused) {
;     ...
;           if (((32 * 44) % G != 0) && ((32 * 18) % G != 0)) { const int rem_ = (32 * 18) % G; const int bxt_ = BXL(); if (rem_ != 0 && bxt_ >= rem_) { GW_DECL; convert_range(lds, (l == 0 ? 17408 : ITEMS_L + 10752), (l == 0 ? 21248 : ITEMS_L + 17408), (bxt_ - rem_) * NWAVES + wv_, (G - rem_) * NWAVES, wv_, lane); convert_range(lds, (l == 0 ? ITEMS_L : 0), (l == 0 ? ITEMS_L + 2816 : 0), (bxt_ - rem_) * NWAVES + wv_, (G - rem_) * NWAVES, wv_, lane); __syncthreads(); } } }
.LBB0_814:
	v_readlane_b32 s2, v255, 29
	v_readlane_b32 s3, v255, 30
	s_and_b64 s[2:3], s[2:3], exec
	s_cselect_b32 s1, 0, 0
	s_cselect_b32 s16, 0, 0
	s_add_i32 s15, s15, s1
	s_cmp_ge_i32 s15, s16
	s_cbranch_scc1 .LBB0_883
	s_mov_b32 s1, s15
	s_mov_b32 s2, 2
	s_mov_b32 s3, 1
	s_mov_b32 s4, 0
	v_bfrev_b32_e32 v0, 1
	v_bfrev_b32_e32 v2, 1

; #define LAS __attribute__((address_space(3)))
; #define GW_DECL const int wv_ = launder_s(g_wave), lane = opaque_lane(), tid = (wv_ << 6) | lane, gw = BXL() * NWAVES + wv_; (void)tid; (void)lane; (void)gw
; #define BXL() ({ int _b = bx; asm volatile("" : "+s"(_b)); _b; })
; __device__ __forceinline__ void convert_range(unsigned char* lds, int lo, int hi, int w, int nworkers, int wave, int lane) {
;     const XItem* tab = (const XItem*)(lds + 8 * 16640);
;     LAS float* scr = (LAS float*)((LAS unsigned char*)lds + wave * 16640);
;     int it = lo + w; if (it >= hi) return;
;     f32x4 v[16]; float gv[16]; ItemPos p = item_load(tab, it, lane, v, gv);
; __global__ void __launch_bounds__(NTHREADS, 2) mega_fwd(KArgs a_unused) {
;     ...
;           if (((32 * 44) % G != 0) && ((32 * 18) % G != 0)) { const int rem_ = (32 * 44) % G; const int bxt_ = BXL(); if (rem_ != 0 && bxt_ >= rem_) { GW_DECL; convert_range(lds, (l == 0 ? ITEMS_L + 2816 : ITEMS_L + 17408), (l == 0 ? ITEMS_L + 5632 : ITEMS_L + 21248), (bxt_ - rem_) * NWAVES + wv_, (G - rem_) * NWAVES, wv_, lane); __syncthreads(); } } }
.LBB0_1366:
	v_readlane_b32 s2, v255, 5
	v_readlane_b32 s3, v255, 6
	s_and_b64 vcc, exec, s[2:3]
	s_cbranch_vccz .LBB0_1439
	v_readlane_b32 s2, v255, 39
	v_readlane_b32 s3, v255, 40
	s_and_b64 vcc, exec, s[2:3]
	s_cbranch_vccnz .LBB0_1439
	v_readlane_b32 s2, v255, 7
	v_readlane_b32 s1, v255, 4
	s_cmp_lt_i32 s2, s1
	v_readlane_b32 s3, v255, 8
	s_cbranch_scc1 .LBB0_1439
	v_readlane_b32 s4, v255, 7
	v_readlane_b32 s5, v255, 8
	s_mov_b32 s3, s4
	v_readlane_b32 s4, v255, 29
	v_readlane_b32 s5, v255, 30
	s_and_b64 s[4:5], s[4:5], exec
	s_mov_b32 s5, 0xa680
	s_movk_i32 s4, 0x4c00
	s_cselect_b32 s14, 0x6980, s5
	v_readlane_b32 s5, v255, 4
	s_cselect_b32 s4, s4, 0x9780
	s_sub_i32 s2, s2, s5
	s_lshl_b32 s2, s2, 3
	s_mov_b32 s1, s64
	s_add_i32 s2, s2, s4
	s_add_i32 s15, s2, s1
	s_cmp_ge_i32 s15, s14
	v_mov_b32 v0, 0
	s_cbranch_scc1 .LBB0_1438
	s_mov_b32 s2, s15
	s_mov_b32 s3, 2
	s_mov_b32 s4, 1
	s_mov_b32 s5, 0
	v_bfrev_b32_e32 v2, 1
	v_bfrev_b32_e32 v3, 1
